# v35 + token pass: the twelve loop-invariant mu loads hoisted out of the row loop (were six serialized load+wait pairs per row)
# baseline (speedup 1.0000x reference)
; __device__ __forceinline__ void p5_row(const P& p, int row, int lane) {
;     unsigned char* ws = p.ws;
;     bf16_t* za = (bf16_t*)(ws + WS_ZA) + (size_t)row * 768;
;     { unsigned* q = (unsigned*)(za + lane * 6); const unsigned w0 = q[0], w1 = q[1], w2 = q[2];
;       float f[6] = {bflo(w0), bfhi(w0), bflo(w1), bfhi(w1), bflo(w2), bfhi(w2)}; float s = 0.f;
; #pragma unroll
;       for (int e = 0; e < 6; ++e) s += f[e] * f[e];
;       const float rstd = 1.0f / sqrtf(wave_sum(s) * (1.f / 384.f) + NORM_EPS); const float* g = p.in[8] + lane * 6;
; #pragma unroll
;       for (int e = 0; e < 6; ++e) f[e] = f[e] * rstd * g[e];
;       q[0] = pkbf(f[0], f[1]); q[1] = pkbf(f[2], f[3]); q[2] = pkbf(f[4], f[5]); }
;     { unsigned* q = (unsigned*)(za + 384 + lane * 4); const unsigned w0 = q[0], w1 = q[1];
;       float f[4] = {bflo(w0), bfhi(w0), bflo(w1), bfhi(w1)}; float s = 0.f;
; #pragma unroll
;       for (int e = 0; e < 4; ++e) s += f[e] * f[e];
;       const float rstd = 1.0f / sqrtf(wave_sum(s) * (1.f / 256.f) + NORM_EPS); const float* g = p.in[10] + lane * 4;
; #pragma unroll
;       for (int e = 0; e < 4; ++e) f[e] = f[e] * rstd * g[e];
;       q[0] = pkbf(f[0], f[1]); q[1] = pkbf(f[2], f[3]); }
;     if (lane < 16) { const float x1 = __uint_as_float((unsigned)za[640 + lane] << 16), x2 = __uint_as_float((unsigned)za[656 + lane] << 16);
;       const float* rp = (const float*)(ws + WS_ROPE) + ((size_t)seq_pos(row) * 16 + lane) * 2; const float c = rp[0], s = rp[1];
;       const unsigned w = pkbf(x1 * c - x2 * s, x1 * s + x2 * c);
;       unsigned* kr = (unsigned*)((bf16_t*)((unsigned char*)p.out + DO_K) + (size_t)row * 768 + 64) + lane;
; #pragma unroll
;       for (int h = 0; h < NH; ++h) kr[h * 48] = w; }
;     { const int pos = seq_pos(row), L = row < TP ? 8192 : 16384;
;       const bf16_t* zl = (const bf16_t*)(ws + WS_ZL) + (size_t)row * 512 + lane * 6;
;       const unsigned* q = (const unsigned*)zl; const unsigned w0 = q[0], w1 = q[1], w2 = q[2];
;       unsigned p0 = 0, p1 = 0, p2 = 0, n0 = 0, n1 = 0, n2 = 0;
;       if (pos > 0) { const unsigned* qq = (const unsigned*)(zl - 512); p0 = qq[0]; p1 = qq[1]; p2 = qq[2]; }
;       if (pos < L - 1) { const unsigned* qq = (const unsigned*)(zl + 512); n0 = qq[0]; n1 = qq[1]; n2 = qq[2]; }
;       const float z[6] = {bflo(w0), bfhi(w0), bflo(w1), bfhi(w1), bflo(w2), bfhi(w2)};
.LBB0_416:
	s_or_b64 exec, exec, s[0:1]
	v_readlane_b32 s0, v237, 63
	v_readlane_b32 s1, v236, 0
	s_and_b64 vcc, exec, s[0:1]
	s_waitcnt lgkmcnt(0)
	s_barrier
	s_cbranch_vccnz .LBB0_451
	v_mbcnt_hi_u32_b32 v0, -1, v210
	v_and_b32_e32 v1, 64, v0
	v_add_u32_e32 v1, 64, v1
	v_xor_b32_e32 v3, 1, v0
	v_cmp_lt_i32_e32 vcc, v3, v1
	v_xor_b32_e32 v4, 2, v0
	v_readlane_b32 s52, v237, 21
	v_cndmask_b32_e32 v3, v0, v3, vcc
	v_cmp_lt_i32_e32 vcc, v4, v1
	v_readlane_b32 s60, v237, 29
	v_readlane_b32 s61, v237, 30
	v_cndmask_b32_e32 v4, v0, v4, vcc
	v_lshlrev_b32_e32 v7, 2, v4
	v_xor_b32_e32 v4, 4, v0
	v_cmp_lt_i32_e32 vcc, v4, v1
	v_mul_u32_u24_e32 v2, 6, v166
	v_readlane_b32 s53, v237, 22
	v_cndmask_b32_e32 v4, v0, v4, vcc
	v_lshlrev_b32_e32 v11, 2, v4
	v_xor_b32_e32 v4, 8, v0
	v_cmp_lt_i32_e32 vcc, v4, v1
	v_readlane_b32 s62, v237, 31
	v_readlane_b32 s63, v237, 32
	v_cndmask_b32_e32 v4, v0, v4, vcc
	v_lshlrev_b32_e32 v36, 2, v4
	v_xor_b32_e32 v4, 16, v0
	v_cmp_lt_i32_e32 vcc, v4, v1
	v_readlane_b32 s64, v237, 33
	v_readlane_b32 s65, v237, 34
	v_cndmask_b32_e32 v4, v0, v4, vcc
	v_lshlrev_b32_e32 v37, 2, v4
	v_xor_b32_e32 v4, 32, v0
	v_cmp_lt_i32_e32 vcc, v4, v1
	s_mov_b64 s[8:9], s[60:61]
	v_mov_b32_e32 v1, 0
	v_cndmask_b32_e32 v0, v0, v4, vcc
	v_lshlrev_b32_e32 v38, 2, v0
	v_lshlrev_b32_e32 v0, 2, v2
	s_mov_b64 s[10:11], s[62:63]
	s_mov_b64 s[0:1], s[52:53]
	v_lshl_add_u64 v[12:13], s[0:1], 0, v[0:1]
	v_lshl_add_u64 v[8:9], s[10:11], 0, v[0:1]
	s_mov_b64 s[0:1], 0x1800
	v_lshl_add_u64 v[18:19], v[8:9], 0, s[0:1]
	s_mov_b64 s[0:1], 0x3600
	s_ashr_i32 s35, s34, 31
	v_lshl_add_u64 v[20:21], v[8:9], 0, s[0:1]
	s_lshl_b64 s[0:1], s[34:35], 10
	v_lshlrev_b32_e32 v0, 1, v2
	s_ashr_i32 s89, s88, 31
	v_mov_b32_e32 v2, 0x600
	v_or_b32_e32 v22, s0, v0
	v_mov_b32_e32 v23, s1
	s_lshl_b64 s[16:17], s[88:89], 10
	s_mul_i32 s14, s34, 0x600
	v_mad_i64_i32 v[26:27], s[0:1], s34, v2, v[0:1]
	s_mul_hi_i32 s3, s34, 0x600
	s_add_u32 s0, s48, s14
	v_readlane_b32 s56, v237, 25
	v_readlane_b32 s57, v237, 26
	v_lshlrev_b32_e32 v4, 2, v166
	v_mov_b32_e32 v5, v1
	s_addc_u32 s1, s49, s3
	v_readlane_b32 s58, v237, 27
	v_readlane_b32 s59, v237, 28
	s_mov_b64 s[12:13], s[64:65]
	s_mov_b64 s[4:5], s[56:57]
	v_mov_b32_e32 v165, v1
	v_mov_b32_e32 v129, v1
	v_lshl_add_u64 v[4:5], s[0:1], 0, v[4:5]
	s_mov_b64 s[0:1], 0x4800080
	v_mov_b32_e32 v2, 0x300
	s_mov_b32 s19, 0
	v_lshlrev_b32_e32 v3, 2, v3
	v_lshl_add_u64 v[14:15], s[4:5], 0, v[164:165]
	v_cmp_lt_u32_e64 s[4:5], 15, v166
	v_lshl_add_u64 v[16:17], s[94:95], 0, v[128:129]
	v_cmp_lt_u32_e64 s[6:7], 21, v166
	v_cmp_gt_u32_e64 s[8:9], 43, v166
	v_cmp_lt_u32_e64 s[10:11], 20, v166
	v_cmp_gt_u32_e64 s[12:13], 42, v166
	v_or_b32_e32 v24, s14, v128
	v_mov_b32_e32 v25, s3
	s_mul_hi_i32 s21, s88, 0x600
	s_mul_i32 s20, s88, 0x600
	v_lshl_or_b32 v28, v166, 1, s14
	v_mov_b32_e32 v29, s3
	v_lshl_add_u64 v[30:31], v[4:5], 0, s[0:1]
	v_mad_i64_i32 v[32:33], s[0:1], s34, v2, v[0:1]
	s_mul_hi_i32 s59, s88, 0x300
	s_mul_i32 s58, s88, 0x300
	s_mov_b32 s3, 0x12000000
	v_mov_b32_e32 v39, 0x358637bd
	s_mov_b32 s24, 0xf800000
	v_mov_b32_e32 v40, 0x260
	s_movk_i32 s25, 0x3fff
	s_mov_b32 s26, s34
	v_readlane_b32 s54, v237, 23
	v_readlane_b32 s55, v237, 24
	v_readlane_b32 s66, v237, 35
	v_readlane_b32 s67, v237, 36
	global_load_dword v180, v[18:19], off
	global_load_dword v181, v[20:21], off
	global_load_dword v182, v[18:19], off offset:4
	global_load_dword v183, v[20:21], off offset:4
	global_load_dword v184, v[18:19], off offset:8
	global_load_dword v185, v[20:21], off offset:8
	global_load_dword v186, v[18:19], off offset:12
	global_load_dword v187, v[20:21], off offset:12
	global_load_dword v188, v[18:19], off offset:16
	global_load_dword v189, v[20:21], off offset:16
	global_load_dword v190, v[18:19], off offset:20
	global_load_dword v191, v[20:21], off offset:20
	s_waitcnt vmcnt(0)
	s_branch .LBB0_419

; __device__ __forceinline__ float fsigmoid(float x) { return __builtin_amdgcn_rcpf(1.f + __builtin_amdgcn_exp2f(-1.4426950408889634f * x)); }
; __device__ __forceinline__ void p5_row(const P& p, int row, int lane) {
;     ...
;       for (int e = 0; e < 6; ++e) { const int c = lane * 6 + e; const float zs = z[e] + mu0[e] * (zp[e] - z[e]) + mu1[e] * (zn[e] - z[e]);
;         float r;
;         if (c < 128) { const float t = __expf(2.f * zs); r = 1.f - 2.f * __builtin_amdgcn_rcpf(t + 1.f); }
;         else if (c < 256) r = zs;
;         else r = fsigmoid(zs);
;         o[e] = r; }
.LBB0_427:
	s_or_b64 exec, exec, s[0:1]
	v_mov_b32_e32 v34, v180
	v_mov_b32_e32 v41, v181
	s_waitcnt vmcnt(0)
	v_lshlrev_b32_e32 v35, 16, v0
	v_lshlrev_b32_e32 v42, 16, v8
	v_lshlrev_b32_e32 v43, 16, v4
	v_sub_f32_e32 v42, v42, v35
	v_sub_f32_e32 v43, v43, v35
	s_waitcnt vmcnt(1)
	v_fmac_f32_e32 v35, v42, v34
	s_waitcnt vmcnt(0)
	v_fmac_f32_e32 v35, v43, v41
	s_and_saveexec_b64 s[0:1], s[6:7]
	s_xor_b64 s[0:1], exec, s[0:1]
	s_cbranch_execz .LBB0_429
	v_mul_f32_e32 v34, 0xbfb8aa3b, v35
	v_exp_f32_e32 v34, v34
	s_nop 0
	v_add_f32_e32 v34, 1.0, v34
	v_rcp_f32_e32 v34, v34
	s_nop 0
	v_cndmask_b32_e64 v34, v34, v35, s[8:9]

; __device__ __forceinline__ float fsigmoid(float x) { return __builtin_amdgcn_rcpf(1.f + __builtin_amdgcn_exp2f(-1.4426950408889634f * x)); }
; __device__ __forceinline__ void p5_row(const P& p, int row, int lane) {
;     ...
;       for (int e = 0; e < 6; ++e) { const int c = lane * 6 + e; const float zs = z[e] + mu0[e] * (zp[e] - z[e]) + mu1[e] * (zn[e] - z[e]);
;         float r;
;         if (c < 128) { const float t = __expf(2.f * zs); r = 1.f - 2.f * __builtin_amdgcn_rcpf(t + 1.f); }
;         else if (c < 256) r = zs;
;         else r = fsigmoid(zs);
;         o[e] = r; }
.LBB0_431:
	s_or_b64 exec, exec, s[0:1]
	v_mov_b32_e32 v41, v182
	v_mov_b32_e32 v42, v183
	v_and_b32_e32 v35, 0xffff0000, v0
	v_and_b32_e32 v0, 0xffff0000, v8
	v_and_b32_e32 v4, 0xffff0000, v4
	v_sub_f32_e32 v0, v0, v35
	v_sub_f32_e32 v4, v4, v35
	s_waitcnt vmcnt(1)
	v_fmac_f32_e32 v35, v0, v41
	s_waitcnt vmcnt(0)
	v_fmac_f32_e32 v35, v4, v42
	s_and_saveexec_b64 s[0:1], s[6:7]
	s_xor_b64 s[0:1], exec, s[0:1]
	s_cbranch_execz .LBB0_433
	v_mul_f32_e32 v0, 0xbfb8aa3b, v35
	v_exp_f32_e32 v0, v0
	s_nop 0
	v_add_f32_e32 v0, 1.0, v0
	v_rcp_f32_e32 v0, v0
	s_nop 0
	v_cndmask_b32_e64 v0, v0, v35, s[8:9]

; __device__ __forceinline__ float fsigmoid(float x) { return __builtin_amdgcn_rcpf(1.f + __builtin_amdgcn_exp2f(-1.4426950408889634f * x)); }
; __device__ __forceinline__ void p5_row(const P& p, int row, int lane) {
;     ...
;       for (int e = 0; e < 6; ++e) { const int c = lane * 6 + e; const float zs = z[e] + mu0[e] * (zp[e] - z[e]) + mu1[e] * (zn[e] - z[e]);
;         float r;
;         if (c < 128) { const float t = __expf(2.f * zs); r = 1.f - 2.f * __builtin_amdgcn_rcpf(t + 1.f); }
;         else if (c < 256) r = zs;
;         else r = fsigmoid(zs);
;         o[e] = r; }
.LBB0_435:
	s_or_b64 exec, exec, s[0:1]
	v_mov_b32_e32 v4, v184
	v_mov_b32_e32 v35, v185
	v_lshlrev_b32_e32 v8, 16, v1
	v_lshlrev_b32_e32 v41, 16, v9
	v_lshlrev_b32_e32 v42, 16, v5
	v_sub_f32_e32 v41, v41, v8
	v_sub_f32_e32 v42, v42, v8
	s_waitcnt vmcnt(1)
	v_fmac_f32_e32 v8, v41, v4
	s_waitcnt vmcnt(0)
	v_fmac_f32_e32 v8, v42, v35
	s_and_saveexec_b64 s[0:1], s[10:11]
	s_xor_b64 s[0:1], exec, s[0:1]
	s_cbranch_execz .LBB0_437
	v_mul_f32_e32 v4, 0xbfb8aa3b, v8
	v_exp_f32_e32 v4, v4
	s_nop 0
	v_add_f32_e32 v4, 1.0, v4
	v_rcp_f32_e32 v4, v4
	s_nop 0
	v_cndmask_b32_e64 v4, v4, v8, s[8:9]

; __device__ __forceinline__ float fsigmoid(float x) { return __builtin_amdgcn_rcpf(1.f + __builtin_amdgcn_exp2f(-1.4426950408889634f * x)); }
; __device__ __forceinline__ void p5_row(const P& p, int row, int lane) {
;     ...
;       for (int e = 0; e < 6; ++e) { const int c = lane * 6 + e; const float zs = z[e] + mu0[e] * (zp[e] - z[e]) + mu1[e] * (zn[e] - z[e]);
;         float r;
;         if (c < 128) { const float t = __expf(2.f * zs); r = 1.f - 2.f * __builtin_amdgcn_rcpf(t + 1.f); }
;         else if (c < 256) r = zs;
;         else r = fsigmoid(zs);
;         o[e] = r; }
.LBB0_439:
	s_or_b64 exec, exec, s[0:1]
	v_mov_b32_e32 v35, v186
	v_mov_b32_e32 v41, v187
	v_and_b32_e32 v8, 0xffff0000, v1
	v_and_b32_e32 v1, 0xffff0000, v9
	v_and_b32_e32 v5, 0xffff0000, v5
	v_sub_f32_e32 v1, v1, v8
	v_sub_f32_e32 v5, v5, v8
	s_waitcnt vmcnt(1)
	v_fmac_f32_e32 v8, v1, v35
	s_waitcnt vmcnt(0)
	v_fmac_f32_e32 v8, v5, v41
	s_and_saveexec_b64 s[0:1], s[10:11]
	s_xor_b64 s[0:1], exec, s[0:1]
	s_cbranch_execz .LBB0_441
	v_mul_f32_e32 v1, 0xbfb8aa3b, v8
	v_exp_f32_e32 v1, v1
	s_nop 0
	v_add_f32_e32 v1, 1.0, v1
	v_rcp_f32_e32 v1, v1
	s_nop 0
	v_cndmask_b32_e64 v1, v1, v8, s[8:9]

; __device__ __forceinline__ float fsigmoid(float x) { return __builtin_amdgcn_rcpf(1.f + __builtin_amdgcn_exp2f(-1.4426950408889634f * x)); }
; __device__ __forceinline__ void p5_row(const P& p, int row, int lane) {
;     ...
;       for (int e = 0; e < 6; ++e) { const int c = lane * 6 + e; const float zs = z[e] + mu0[e] * (zp[e] - z[e]) + mu1[e] * (zn[e] - z[e]);
;         float r;
;         if (c < 128) { const float t = __expf(2.f * zs); r = 1.f - 2.f * __builtin_amdgcn_rcpf(t + 1.f); }
;         else if (c < 256) r = zs;
;         else r = fsigmoid(zs);
;         o[e] = r; }
.LBB0_443:
	s_or_b64 exec, exec, s[0:1]
	v_mov_b32_e32 v5, v188
	v_mov_b32_e32 v9, v189
	v_lshlrev_b32_e32 v8, 16, v2
	v_lshlrev_b32_e32 v35, 16, v10
	v_lshlrev_b32_e32 v41, 16, v6
	v_sub_f32_e32 v35, v35, v8
	v_sub_f32_e32 v41, v41, v8
	s_waitcnt vmcnt(1)
	v_fmac_f32_e32 v8, v35, v5
	s_waitcnt vmcnt(0)
	v_fmac_f32_e32 v8, v41, v9
	s_and_saveexec_b64 s[0:1], s[10:11]
	s_xor_b64 s[0:1], exec, s[0:1]
	s_cbranch_execz .LBB0_445
	v_mul_f32_e32 v5, 0xbfb8aa3b, v8
	v_exp_f32_e32 v5, v5
	s_nop 0
	v_add_f32_e32 v5, 1.0, v5
	v_rcp_f32_e32 v5, v5
	s_nop 0
	v_cndmask_b32_e64 v5, v5, v8, s[12:13]

; __device__ __forceinline__ float fsigmoid(float x) { return __builtin_amdgcn_rcpf(1.f + __builtin_amdgcn_exp2f(-1.4426950408889634f * x)); }
; __device__ __forceinline__ void p5_row(const P& p, int row, int lane) {
;     ...
;       for (int e = 0; e < 6; ++e) { const int c = lane * 6 + e; const float zs = z[e] + mu0[e] * (zp[e] - z[e]) + mu1[e] * (zn[e] - z[e]);
;         float r;
;         if (c < 128) { const float t = __expf(2.f * zs); r = 1.f - 2.f * __builtin_amdgcn_rcpf(t + 1.f); }
;         else if (c < 256) r = zs;
;         else r = fsigmoid(zs);
;         o[e] = r; }
.LBB0_447:
	s_or_b64 exec, exec, s[0:1]
	v_mov_b32_e32 v9, v190
	v_mov_b32_e32 v35, v191
	v_and_b32_e32 v8, 0xffff0000, v2
	v_and_b32_e32 v2, 0xffff0000, v10
	v_and_b32_e32 v6, 0xffff0000, v6
	v_sub_f32_e32 v2, v2, v8
	v_sub_f32_e32 v6, v6, v8
	s_waitcnt vmcnt(1)
	v_fmac_f32_e32 v8, v2, v9
	s_waitcnt vmcnt(0)
	v_fmac_f32_e32 v8, v6, v35
	s_and_saveexec_b64 s[0:1], s[10:11]
	s_xor_b64 s[0:1], exec, s[0:1]
	s_cbranch_execz .LBB0_449
	v_mul_f32_e32 v2, 0xbfb8aa3b, v8
	v_exp_f32_e32 v2, v2
	s_nop 0
	v_add_f32_e32 v2, 1.0, v2
	v_rcp_f32_e32 v2, v2
	s_nop 0
	v_cndmask_b32_e64 v2, v2, v8, s[12:13]
